# D7: staging pieces placed after PV MFMAs 1,2,3,4 (instead of 1,3,5,7) in the diff, FoX, selected and window loops
# speedup vs baseline: 1.0198x; 1.0020x over previous
.LBB0_672:
	s_nop 7
	v_exp_f32_e32 v2, v48
	v_exp_f32_e32 v3, v49
	v_exp_f32_e32 v4, v50
	v_exp_f32_e32 v5, v51
	v_add_f32_e32 v0, 0, v2
	v_exp_f32_e32 v6, v52
	v_add_f32_e32 v0, v3, v0
	v_exp_f32_e32 v7, v53
	v_add_f32_e32 v0, v4, v0
	v_exp_f32_e32 v8, v54
	v_add_f32_e32 v0, v5, v0
	v_exp_f32_e32 v9, v55
	v_add_f32_e32 v0, v6, v0
	v_add_f32_e32 v0, v7, v0
	v_exp_f32_e32 v50, v60
	v_exp_f32_e32 v60, v70
	v_add3_u32 v70, s6, v143, v145
	v_add_f32_e32 v0, v8, v0
	v_exp_f32_e32 v51, v61
	v_exp_f32_e32 v61, v71
	v_add_u32_e32 v71, 0x2000, v70
	v_add_f32_e32 v0, v9, v0
	v_cvt_pk_bf16_f32 v2, v2, v3
	v_cvt_pk_bf16_f32 v3, v4, v5
	v_cvt_pk_bf16_f32 v4, v6, v7
	v_cvt_pk_bf16_f32 v5, v8, v9
	ds_read2_b64 v[6:9], v71 offset0:128 offset1:130
	ds_read2_b64 v[10:13], v71 offset0:132 offset1:134
	v_add_u32_e32 v70, 0x3000, v70
	s_waitcnt lgkmcnt(1)
	v_mfma_f32_32x32x16_bf16 v[32:47], v[6:9], v[2:5], v[32:47]
	s_mul_i32 s16, s4, 0x4a00
	v_or_b32_e32 v252, s16, v125
	v_add_u32_e32 v253, v252, v137
	s_waitcnt vmcnt(3)
	ds_write_b128 v253, v[100:103]
	global_load_dwordx4 v[100:103], v228, s[10:11]
	ds_read2_b64 v[6:9], v70 offset0:160 offset1:162
	v_exp_f32_e32 v14, v56
	v_exp_f32_e32 v15, v57
	v_exp_f32_e32 v48, v58
	v_exp_f32_e32 v49, v59
	v_exp_f32_e32 v52, v62
	v_exp_f32_e32 v53, v63
	s_waitcnt lgkmcnt(0)
	v_mfma_f32_32x32x16_bf16 v[16:31], v[6:9], v[2:5], v[16:31]
	v_add3_u32 v253, v252, v138, s33
	s_waitcnt vmcnt(2)
	ds_write2_b64 v253, v[104:105], v[106:107] offset1:1
	global_load_dwordx4 v[104:107], v230, s[22:23]
	ds_read2_b64 v[6:9], v70 offset0:164 offset1:166
	v_cvt_pk_bf16_f32 v2, v14, v15
	v_cvt_pk_bf16_f32 v3, v48, v49
	v_cvt_pk_bf16_f32 v4, v50, v51
	v_cvt_pk_bf16_f32 v5, v52, v53
	v_exp_f32_e32 v54, v64
	v_exp_f32_e32 v55, v65
	s_waitcnt lgkmcnt(0)
	v_mfma_f32_32x32x16_bf16 v[16:31], v[6:9], v[2:5], v[16:31]
	v_add_u32_e32 v253, v252, v139
	s_waitcnt vmcnt(3)
	ds_write_b128 v253, v[108:111]
	global_load_dwordx4 v[108:111], v229, s[10:11]
	ds_read2_b64 v[6:9], v71 offset0:136 offset1:138
	v_exp_f32_e32 v56, v66
	v_exp_f32_e32 v57, v67
	v_exp_f32_e32 v58, v68
	v_exp_f32_e32 v59, v69
	v_add_f32_e32 v0, v14, v0
	v_add_f32_e32 v0, v15, v0
	v_mfma_f32_32x32x16_bf16 v[32:47], v[10:13], v[2:5], v[32:47]
	v_add3_u32 v253, v252, v140, s33
	s_waitcnt vmcnt(3)
	ds_write2_b64 v253, v[112:113], v[114:115] offset1:1
	global_load_dwordx4 v[112:115], v231, s[22:23]
	s_add_u32 s10, s10, 0x2000
	s_addc_u32 s11, s11, 0
	s_add_u32 s22, s22, 0x80
	s_addc_u32 s23, s23, 0
	v_cvt_pk_bf16_f32 v2, v54, v55
	v_cvt_pk_bf16_f32 v3, v56, v57
	v_cvt_pk_bf16_f32 v4, v58, v59
	v_cvt_pk_bf16_f32 v5, v60, v61
	v_add_f32_e32 v0, v48, v0
	v_add_f32_e32 v0, v49, v0
	v_exp_f32_e32 v62, v72
	s_waitcnt lgkmcnt(0)
	v_mfma_f32_32x32x16_bf16 v[32:47], v[6:9], v[2:5], v[32:47]
	ds_read2_b64 v[6:9], v70 offset0:168 offset1:170
	v_exp_f32_e32 v63, v73
	v_exp_f32_e32 v64, v74
	v_exp_f32_e32 v65, v75
	v_exp_f32_e32 v66, v76
	v_exp_f32_e32 v67, v77
	v_exp_f32_e32 v68, v78
	s_waitcnt lgkmcnt(0)
	v_mfma_f32_32x32x16_bf16 v[16:31], v[6:9], v[2:5], v[16:31]
	ds_read2_b64 v[6:9], v71 offset0:140 offset1:142
	v_exp_f32_e32 v69, v79
	v_add_f32_e32 v0, v50, v0
	v_add_f32_e32 v0, v51, v0
	v_add_f32_e32 v0, v52, v0
	v_add_f32_e32 v0, v53, v0
	v_cvt_pk_bf16_f32 v2, v62, v63
	v_cvt_pk_bf16_f32 v3, v64, v65
	v_cvt_pk_bf16_f32 v4, v66, v67
	v_cvt_pk_bf16_f32 v5, v68, v69
	v_add_f32_e32 v0, v54, v0
	v_add_f32_e32 v0, v55, v0
	s_waitcnt lgkmcnt(0)
	v_mfma_f32_32x32x16_bf16 v[32:47], v[6:9], v[2:5], v[32:47]
	ds_read2_b64 v[6:9], v70 offset0:172 offset1:174
	v_add_f32_e32 v0, v56, v0
	v_add_f32_e32 v0, v57, v0
	v_add_f32_e32 v0, v58, v0
	v_add_f32_e32 v0, v59, v0
	v_add_f32_e32 v0, v60, v0
	v_add_f32_e32 v0, v61, v0
	v_add_f32_e32 v0, v62, v0
	v_add_f32_e32 v0, v63, v0
	s_waitcnt lgkmcnt(0)
	v_mfma_f32_32x32x16_bf16 v[16:31], v[6:9], v[2:5], v[16:31]
	s_and_saveexec_b64 s[0:1], s[38:39]
	s_cbranch_execz .Ld5f_noga
	s_waitcnt vmcnt(4)
	v_xor_b32_e32 v239, 0x80000000, v99
	v_xor_b32_e32 v238, 0x80000000, v98
	v_xor_b32_e32 v237, 0x80000000, v97
	v_xor_b32_e32 v236, 0x80000000, v96
	v_add_u32_e32 v253, s16, v119
	ds_write_b128 v253, v[236:239] offset:18432
	global_load_dwordx4 v[96:99], v228, s[24:25]

.LBB0_705:
	s_nop 7
	v_exp_f32_e32 v2, v80
	v_exp_f32_e32 v3, v81
	v_exp_f32_e32 v4, v82
	v_exp_f32_e32 v5, v83
	v_add_f32_e32 v0, 0, v2
	v_exp_f32_e32 v6, v84
	v_add_f32_e32 v0, v3, v0
	v_exp_f32_e32 v7, v85
	v_add_f32_e32 v0, v4, v0
	v_exp_f32_e32 v8, v86
	v_add_f32_e32 v0, v5, v0
	v_exp_f32_e32 v9, v87
	v_add_f32_e32 v0, v6, v0
	v_add_f32_e32 v0, v7, v0
	v_add3_u32 v86, s14, v147, v149
	v_add_f32_e32 v0, v8, v0
	v_add_u32_e32 v87, 0x2000, v86
	v_add_f32_e32 v0, v9, v0
	v_cvt_pk_bf16_f32 v2, v2, v3
	v_cvt_pk_bf16_f32 v3, v4, v5
	v_cvt_pk_bf16_f32 v4, v6, v7
	v_cvt_pk_bf16_f32 v5, v8, v9
	ds_read2_b64 v[6:9], v87 offset0:128 offset1:130
	ds_read2_b64 v[10:13], v87 offset0:132 offset1:134
	v_add_u32_e32 v86, 0x3000, v86
	s_waitcnt lgkmcnt(1)
	v_mfma_f32_32x32x16_bf16 v[32:47], v[6:9], v[2:5], v[32:47]
	s_mul_i32 s1, s9, 0x4a00
	v_or_b32_e32 v184, s1, v131
	v_add_u32_e32 v185, v184, v133
	s_waitcnt vmcnt(3)
	ds_write_b128 v185, v[108:111]
	global_load_dwordx4 v[108:111], v180, s[10:11]
	ds_read2_b64 v[6:9], v86 offset0:160 offset1:162
	v_exp_f32_e32 v14, v88
	v_exp_f32_e32 v15, v89
	v_exp_f32_e32 v80, v90
	v_exp_f32_e32 v81, v91
	v_exp_f32_e32 v82, v92
	v_exp_f32_e32 v83, v93
	s_waitcnt lgkmcnt(0)
	v_mfma_f32_32x32x16_bf16 v[16:31], v[6:9], v[2:5], v[16:31]
	v_add3_u32 v185, v184, v144, s33
	s_waitcnt vmcnt(2)
	ds_write2_b64 v185, v[104:105], v[106:107] offset1:1
	global_load_dwordx4 v[104:107], v182, s[16:17]
	ds_read2_b64 v[6:9], v86 offset0:164 offset1:166
	v_exp_f32_e32 v84, v94
	v_exp_f32_e32 v85, v95
	v_cvt_pk_bf16_f32 v2, v14, v15
	v_cvt_pk_bf16_f32 v3, v80, v81
	v_cvt_pk_bf16_f32 v4, v82, v83
	v_cvt_pk_bf16_f32 v5, v84, v85
	v_exp_f32_e32 v64, v64
	v_exp_f32_e32 v65, v65
	s_waitcnt lgkmcnt(0)
	v_mfma_f32_32x32x16_bf16 v[16:31], v[6:9], v[2:5], v[16:31]
	v_add_u32_e32 v185, v184, v145
	s_waitcnt vmcnt(3)
	ds_write_b128 v185, v[112:115]
	global_load_dwordx4 v[112:115], v181, s[10:11]
	ds_read2_b64 v[6:9], v87 offset0:136 offset1:138
	v_exp_f32_e32 v66, v66
	v_exp_f32_e32 v67, v67
	v_exp_f32_e32 v68, v68
	v_exp_f32_e32 v69, v69
	v_exp_f32_e32 v70, v70
	v_exp_f32_e32 v71, v71
	v_mfma_f32_32x32x16_bf16 v[32:47], v[10:13], v[2:5], v[32:47]
	v_add3_u32 v185, v184, v146, s33
	s_waitcnt vmcnt(3)
	ds_write2_b64 v185, v[116:117], v[118:119] offset1:1
	global_load_dwordx4 v[116:119], v183, s[16:17]
	s_add_u32 s10, s10, 0x2000
	s_addc_u32 s11, s11, 0
	s_add_u32 s16, s16, 0x80
	s_addc_u32 s17, s17, 0
	v_cvt_pk_bf16_f32 v2, v64, v65
	v_cvt_pk_bf16_f32 v3, v66, v67
	v_cvt_pk_bf16_f32 v4, v68, v69
	v_cvt_pk_bf16_f32 v5, v70, v71
	v_add_f32_e32 v0, v14, v0
	v_add_f32_e32 v0, v15, v0
	v_add_f32_e32 v0, v80, v0
	s_waitcnt lgkmcnt(0)
	v_mfma_f32_32x32x16_bf16 v[32:47], v[6:9], v[2:5], v[32:47]
	ds_read2_b64 v[6:9], v86 offset0:168 offset1:170
	v_add_f32_e32 v0, v81, v0
	v_exp_f32_e32 v72, v72
	v_exp_f32_e32 v73, v73
	v_exp_f32_e32 v74, v74
	v_exp_f32_e32 v75, v75
	v_exp_f32_e32 v76, v76
	s_waitcnt lgkmcnt(0)
	v_mfma_f32_32x32x16_bf16 v[16:31], v[6:9], v[2:5], v[16:31]
	ds_read2_b64 v[6:9], v87 offset0:140 offset1:142
	v_exp_f32_e32 v77, v77
	v_exp_f32_e32 v78, v78
	v_exp_f32_e32 v79, v79
	v_add_f32_e32 v0, v82, v0
	v_add_f32_e32 v0, v83, v0
	v_add_f32_e32 v0, v84, v0
	v_add_f32_e32 v0, v85, v0
	v_cvt_pk_bf16_f32 v2, v72, v73
	v_cvt_pk_bf16_f32 v3, v74, v75
	v_cvt_pk_bf16_f32 v4, v76, v77
	v_cvt_pk_bf16_f32 v5, v78, v79
	v_add_f32_e32 v0, v64, v0
	v_add_f32_e32 v0, v65, v0
	s_waitcnt lgkmcnt(0)
	v_mfma_f32_32x32x16_bf16 v[32:47], v[6:9], v[2:5], v[32:47]
	ds_read2_b64 v[6:9], v86 offset0:172 offset1:174
	v_add_f32_e32 v0, v66, v0
	v_add_f32_e32 v0, v67, v0
	v_add_f32_e32 v0, v68, v0
	v_add_f32_e32 v0, v69, v0
	v_add_f32_e32 v0, v70, v0
	v_add_f32_e32 v0, v71, v0
	v_add_f32_e32 v0, v72, v0
	v_add_f32_e32 v0, v73, v0
	s_waitcnt lgkmcnt(0)
	v_mfma_f32_32x32x16_bf16 v[16:31], v[6:9], v[2:5], v[16:31]
	v_add_f32_e32 v0, v74, v0
	v_add_f32_e32 v0, v75, v0
	v_add_f32_e32 v0, v76, v0
	v_add_f32_e32 v0, v77, v0
	v_add_f32_e32 v0, v78, v0
	v_add_f32_e32 v0, v79, v0
	v_add_f32_e32 v152, v152, v0
	v_cmp_lt_f32_e32 vcc, s20, v0
	s_cbranch_vccz .LBB0_707
	v_mov_b32_e32 v2, v0
	s_nop 1
	v_permlane32_swap_b32_e32 v0, v2
	v_add_f32_e32 v0, v0, v2
	v_log_f32_e32 v2, v0
	v_cmp_lt_f32_e32 vcc, s20, v0
	s_nop 1
	v_cndmask_b32_e32 v2, 0, v2, vcc
	v_exp_f32_e64 v0, -v2
	v_add_f32_e32 v153, v153, v2
	v_xor_b32_e32 v63, 0x80000000, v153
	v_mov_b32_e32 v62, v63
	v_mul_f32_e32 v152, v152, v0
	v_pk_mul_f32 v[46:47], v[46:47], v[0:1] op_sel_hi:[1,0]
	v_pk_mul_f32 v[44:45], v[44:45], v[0:1] op_sel_hi:[1,0]
	v_pk_mul_f32 v[42:43], v[42:43], v[0:1] op_sel_hi:[1,0]
	v_pk_mul_f32 v[40:41], v[40:41], v[0:1] op_sel_hi:[1,0]
	v_pk_mul_f32 v[38:39], v[38:39], v[0:1] op_sel_hi:[1,0]
	v_pk_mul_f32 v[36:37], v[36:37], v[0:1] op_sel_hi:[1,0]
	v_pk_mul_f32 v[34:35], v[34:35], v[0:1] op_sel_hi:[1,0]
	v_pk_mul_f32 v[32:33], v[32:33], v[0:1] op_sel_hi:[1,0]
	v_pk_mul_f32 v[30:31], v[30:31], v[0:1] op_sel_hi:[1,0]
	v_pk_mul_f32 v[28:29], v[28:29], v[0:1] op_sel_hi:[1,0]
	v_pk_mul_f32 v[26:27], v[26:27], v[0:1] op_sel_hi:[1,0]
	v_pk_mul_f32 v[24:25], v[24:25], v[0:1] op_sel_hi:[1,0]
	v_pk_mul_f32 v[22:23], v[22:23], v[0:1] op_sel_hi:[1,0]
	v_pk_mul_f32 v[20:21], v[20:21], v[0:1] op_sel_hi:[1,0]
	v_pk_mul_f32 v[18:19], v[18:19], v[0:1] op_sel_hi:[1,0]
	v_pk_mul_f32 v[16:17], v[16:17], v[0:1] op_sel_hi:[1,0]
	v_mov_b32_e32 v61, v63
	v_mov_b32_e32 v60, v63
	v_mov_b32_e32 v59, v63
	v_mov_b32_e32 v58, v63
	v_mov_b32_e32 v57, v63
	v_mov_b32_e32 v56, v63
	v_mov_b32_e32 v55, v63
	v_mov_b32_e32 v54, v63
	v_mov_b32_e32 v53, v63
	v_mov_b32_e32 v52, v63
	v_mov_b32_e32 v51, v63
	v_mov_b32_e32 v50, v63
	v_mov_b32_e32 v49, v63
	v_mov_b32_e32 v48, v63
	s_branch .LBB0_707

.LBB0_919:
	s_nop 7
	v_exp_f32_e32 v66, v66
	v_exp_f32_e32 v67, v67
	v_exp_f32_e32 v68, v68
	v_exp_f32_e32 v69, v69
	v_add_f32_e32 v147, 0, v66
	v_exp_f32_e32 v70, v70
	v_add_f32_e32 v147, v67, v147
	v_exp_f32_e32 v71, v71
	v_add_f32_e32 v147, v68, v147
	v_exp_f32_e32 v72, v72
	v_add_f32_e32 v147, v69, v147
	v_exp_f32_e32 v73, v73
	v_add_f32_e32 v147, v70, v147
	v_exp_f32_e32 v74, v74
	v_add_f32_e32 v147, v71, v147
	v_exp_f32_e32 v75, v75
	v_add_f32_e32 v147, v72, v147
	v_exp_f32_e32 v76, v76
	v_add_f32_e32 v147, v73, v147
	v_exp_f32_e32 v77, v77
	v_add_f32_e32 v147, v74, v147
	v_exp_f32_e32 v78, v78
	v_add_f32_e32 v147, v75, v147
	v_exp_f32_e32 v79, v79
	v_add_f32_e32 v147, v76, v147
	v_exp_f32_e32 v80, v80
	v_add_f32_e32 v147, v77, v147
	v_exp_f32_e32 v81, v81
	v_add_f32_e32 v147, v78, v147
	v_exp_f32_e32 v148, v50
	v_add_f32_e32 v147, v79, v147
	v_exp_f32_e32 v149, v51
	v_add_f32_e32 v50, v80, v147
	v_add_f32_e32 v50, v81, v50
	v_add3_u32 v153, s22, v181, v187
	v_add_f32_e32 v50, v148, v50
	v_add_u32_e32 v154, 0x2000, v153
	v_add_f32_e32 v147, v149, v50
	v_exp_f32_e32 v150, v52
	v_exp_f32_e32 v151, v53
	ds_read2_b64 v[50:53], v154 offset0:128 offset1:130
	v_add_u32_e32 v153, 0x3000, v153
	v_exp_f32_e32 v152, v54
	v_cvt_pk_bf16_f32 v54, v66, v67
	v_cvt_pk_bf16_f32 v66, v68, v69
	v_cvt_pk_bf16_f32 v67, v70, v71
	v_cvt_pk_bf16_f32 v68, v72, v73
	ds_read2_b64 v[70:73], v153 offset0:160 offset1:162
	v_cndmask_b32_e64 v69, 0, v68, s[0:1]
	v_cndmask_b32_e64 v68, 0, v67, s[0:1]
	v_cndmask_b32_e64 v67, 0, v66, s[0:1]
	v_cndmask_b32_e64 v66, 0, v54, s[0:1]
	v_exp_f32_e32 v155, v55
	v_exp_f32_e32 v193, v56
	s_waitcnt lgkmcnt(1)
	v_mfma_f32_32x32x16_bf16 v[18:33], v[50:53], v[66:69], v[18:33]
	s_mul_i32 s23, s17, 0x4a00
	v_or_b32_e32 v252, s23, v129
	v_add_u32_e32 v253, v252, v131
	s_waitcnt vmcnt(3)
	ds_write_b128 v253, v[98:101]
	global_load_dwordx4 v[98:101], v228, s[12:13]
	v_add_f32_e32 v50, v150, v147
	v_add_f32_e32 v50, v151, v50
	v_add_f32_e32 v147, v152, v50
	ds_read2_b64 v[50:53], v154 offset0:132 offset1:134
	v_exp_f32_e32 v194, v57
	v_cvt_pk_bf16_f32 v54, v74, v75
	v_cvt_pk_bf16_f32 v55, v76, v77
	s_waitcnt lgkmcnt(1)
	v_mfma_f32_32x32x16_bf16 v[2:17], v[70:73], v[66:69], v[2:17]
	v_add3_u32 v253, v252, v185, s33
	s_waitcnt vmcnt(2)
	ds_write2_b64 v253, v[102:103], v[104:105] offset1:1
	global_load_dwordx4 v[102:105], v230, s[24:25]
	ds_read2_b64 v[66:69], v153 offset0:164 offset1:166
	v_cvt_pk_bf16_f32 v56, v78, v79
	v_cvt_pk_bf16_f32 v57, v80, v81
	v_cndmask_b32_e64 v57, 0, v57, s[0:1]
	v_cndmask_b32_e64 v56, 0, v56, s[0:1]
	v_cndmask_b32_e64 v55, 0, v55, s[0:1]
	v_cndmask_b32_e64 v54, 0, v54, s[0:1]
	v_exp_f32_e32 v58, v58
	v_exp_f32_e32 v59, v59
	s_waitcnt lgkmcnt(1)
	v_mfma_f32_32x32x16_bf16 v[18:33], v[50:53], v[54:57], v[18:33]
	v_add_u32_e32 v253, v252, v180
	s_waitcnt vmcnt(3)
	ds_write_b128 v253, v[106:109]
	global_load_dwordx4 v[106:109], v229, s[12:13]
	v_add_f32_e32 v50, v155, v147
	v_add_f32_e32 v50, v193, v50
	v_add_f32_e32 v50, v194, v50
	v_add_f32_e32 v70, v58, v50
	ds_read2_b64 v[50:53], v154 offset0:136 offset1:138
	v_exp_f32_e32 v60, v60
	v_exp_f32_e32 v71, v61
	s_waitcnt lgkmcnt(1)
	v_mfma_f32_32x32x16_bf16 v[2:17], v[66:69], v[54:57], v[2:17]
	v_add3_u32 v253, v252, v186, s33
	s_waitcnt vmcnt(3)
	ds_write2_b64 v253, v[110:111], v[112:113] offset1:1
	global_load_dwordx4 v[110:113], v231, s[24:25]
	s_add_u32 s12, s12, 0x2000
	s_addc_u32 s13, s13, 0
	s_add_u32 s24, s24, 0x80
	s_addc_u32 s25, s25, 0
	ds_read2_b64 v[66:69], v153 offset0:168 offset1:170
	v_cvt_pk_bf16_f32 v54, v148, v149
	v_cvt_pk_bf16_f32 v55, v150, v151
	v_cvt_pk_bf16_f32 v56, v152, v155
	v_cvt_pk_bf16_f32 v57, v193, v194
	v_cndmask_b32_e64 v57, 0, v57, s[0:1]
	v_cndmask_b32_e64 v56, 0, v56, s[0:1]
	v_cndmask_b32_e64 v55, 0, v55, s[0:1]
	v_cndmask_b32_e64 v54, 0, v54, s[0:1]
	v_exp_f32_e32 v62, v62
	v_exp_f32_e32 v63, v63
	s_waitcnt lgkmcnt(1)
	v_mfma_f32_32x32x16_bf16 v[18:33], v[50:53], v[54:57], v[18:33]
	v_add_f32_e32 v50, v59, v70
	v_add_f32_e32 v70, v60, v50
	ds_read2_b64 v[50:53], v154 offset0:140 offset1:142
	v_exp_f32_e32 v64, v64
	v_exp_f32_e32 v65, v65
	s_waitcnt lgkmcnt(1)
	v_mfma_f32_32x32x16_bf16 v[2:17], v[66:69], v[54:57], v[2:17]
	v_cvt_pk_bf16_f32 v54, v58, v59
	v_cvt_pk_bf16_f32 v55, v60, v71
	ds_read2_b64 v[58:61], v153 offset0:172 offset1:174
	v_cvt_pk_bf16_f32 v56, v62, v63
	v_cvt_pk_bf16_f32 v57, v64, v65
	v_cndmask_b32_e64 v57, 0, v57, s[0:1]
	v_cndmask_b32_e64 v56, 0, v56, s[0:1]
	v_cndmask_b32_e64 v55, 0, v55, s[0:1]
	v_cndmask_b32_e64 v54, 0, v54, s[0:1]
	s_waitcnt lgkmcnt(1)
	s_nop 0
	v_mfma_f32_32x32x16_bf16 v[18:33], v[50:53], v[54:57], v[18:33]
	v_add_f32_e32 v50, v71, v70
	v_add_f32_e32 v50, v62, v50
	v_add_f32_e32 v50, v63, v50
	v_add_f32_e32 v50, v64, v50
	v_add_f32_e32 v50, v65, v50
	v_cndmask_b32_e64 v50, 0, v50, s[0:1]
	v_add_f32_e32 v133, v133, v50
	s_waitcnt lgkmcnt(0)
	v_mfma_f32_32x32x16_bf16 v[2:17], v[58:61], v[54:57], v[2:17]
	v_cmp_lt_f32_e32 vcc, s20, v50
	s_cbranch_vccz .LBB0_921
	v_mov_b32_e32 v34, v50
	s_nop 1
	v_permlane32_swap_b32_e32 v50, v34
	v_add_f32_e32 v34, v50, v34
	v_log_f32_e32 v35, v34
	v_cmp_lt_f32_e32 vcc, s20, v34
	s_nop 1
	v_cndmask_b32_e32 v35, 0, v35, vcc
	v_exp_f32_e64 v34, -v35
	v_add_f32_e32 v135, v135, v35
	v_xor_b32_e32 v49, 0x80000000, v135
	v_mov_b32_e32 v48, v49
	v_mul_f32_e32 v133, v133, v34
	v_pk_mul_f32 v[32:33], v[32:33], v[34:35] op_sel_hi:[1,0]
	v_pk_mul_f32 v[30:31], v[30:31], v[34:35] op_sel_hi:[1,0]
	v_pk_mul_f32 v[28:29], v[28:29], v[34:35] op_sel_hi:[1,0]
	v_pk_mul_f32 v[26:27], v[26:27], v[34:35] op_sel_hi:[1,0]
	v_pk_mul_f32 v[24:25], v[24:25], v[34:35] op_sel_hi:[1,0]
	v_pk_mul_f32 v[22:23], v[22:23], v[34:35] op_sel_hi:[1,0]
	v_pk_mul_f32 v[20:21], v[20:21], v[34:35] op_sel_hi:[1,0]
	v_pk_mul_f32 v[18:19], v[18:19], v[34:35] op_sel_hi:[1,0]
	v_pk_mul_f32 v[16:17], v[16:17], v[34:35] op_sel_hi:[1,0]
	v_pk_mul_f32 v[14:15], v[14:15], v[34:35] op_sel_hi:[1,0]
	v_pk_mul_f32 v[12:13], v[12:13], v[34:35] op_sel_hi:[1,0]
	v_pk_mul_f32 v[10:11], v[10:11], v[34:35] op_sel_hi:[1,0]
	v_pk_mul_f32 v[8:9], v[8:9], v[34:35] op_sel_hi:[1,0]
	v_pk_mul_f32 v[6:7], v[6:7], v[34:35] op_sel_hi:[1,0]
	v_pk_mul_f32 v[4:5], v[4:5], v[34:35] op_sel_hi:[1,0]
	v_pk_mul_f32 v[2:3], v[2:3], v[34:35] op_sel_hi:[1,0]
	v_mov_b32_e32 v47, v49
	v_mov_b32_e32 v46, v49
	v_mov_b32_e32 v45, v49
	v_mov_b32_e32 v44, v49
	v_mov_b32_e32 v43, v49
	v_mov_b32_e32 v42, v49
	v_mov_b32_e32 v41, v49
	v_mov_b32_e32 v40, v49
	v_mov_b32_e32 v39, v49
	v_mov_b32_e32 v38, v49
	v_mov_b32_e32 v37, v49
	v_mov_b32_e32 v36, v49
	v_mov_b32_e32 v35, v49
	v_mov_b32_e32 v34, v49
	s_branch .LBB0_921

.LBB0_936:
	s_nop 4
	v_exp_f32_e32 v66, v66
	v_exp_f32_e32 v67, v67
	v_exp_f32_e32 v68, v68
	v_exp_f32_e32 v69, v69
	v_add_f32_e32 v138, 0, v66
	v_exp_f32_e32 v70, v70
	v_add_f32_e32 v138, v67, v138
	v_exp_f32_e32 v71, v71
	v_add_f32_e32 v138, v68, v138
	v_exp_f32_e32 v72, v72
	v_add_f32_e32 v138, v69, v138
	v_exp_f32_e32 v73, v73
	v_add_f32_e32 v138, v70, v138
	v_exp_f32_e32 v74, v74
	v_add_f32_e32 v138, v71, v138
	v_exp_f32_e32 v75, v75
	v_add_f32_e32 v138, v72, v138
	v_exp_f32_e32 v76, v76
	v_add_f32_e32 v138, v73, v138
	v_exp_f32_e32 v77, v77
	v_add_f32_e32 v138, v74, v138
	v_exp_f32_e32 v78, v78
	v_add_f32_e32 v138, v75, v138
	v_exp_f32_e32 v79, v79
	v_add_f32_e32 v138, v76, v138
	v_exp_f32_e32 v80, v80
	v_add_f32_e32 v138, v77, v138
	v_exp_f32_e32 v81, v81
	v_add_f32_e32 v138, v78, v138
	v_exp_f32_e32 v139, v50
	v_add_f32_e32 v138, v79, v138
	v_add_f32_e32 v138, v80, v138
	v_add_f32_e32 v138, v81, v138
	v_add_f32_e32 v50, v139, v138
	v_exp_f32_e32 v138, v52
	v_cvt_pk_bf16_f32 v52, v66, v67
	v_add3_u32 v66, s16, v181, v187
	v_add_u32_e32 v67, 0x2000, v66
	v_exp_f32_e32 v143, v56
	v_exp_f32_e32 v144, v57
	v_exp_f32_e32 v145, v58
	v_exp_f32_e32 v147, v59
	v_exp_f32_e32 v148, v60
	v_exp_f32_e32 v149, v61
	v_exp_f32_e32 v150, v62
	v_exp_f32_e32 v151, v63
	ds_read2_b64 v[56:59], v67 offset0:128 offset1:130
	ds_read2_b64 v[60:63], v67 offset0:132 offset1:134
	v_exp_f32_e32 v140, v53
	v_exp_f32_e32 v141, v54
	v_exp_f32_e32 v142, v55
	v_cvt_pk_bf16_f32 v53, v68, v69
	v_cvt_pk_bf16_f32 v54, v70, v71
	v_cvt_pk_bf16_f32 v55, v72, v73
	v_add_u32_e32 v66, 0x3000, v66
	v_exp_f32_e32 v51, v51
	s_waitcnt lgkmcnt(1)
	v_mfma_f32_32x32x16_bf16 v[18:33], v[56:59], v[52:55], v[18:33]
	s_mul_i32 s22, s15, 0x4a00
	v_or_b32_e32 v252, s22, v129
	v_add_u32_e32 v253, v252, v131
	s_waitcnt vmcnt(3)
	ds_write_b128 v253, v[98:101]
	global_load_dwordx4 v[98:101], v228, s[12:13]
	ds_read2_b64 v[56:59], v66 offset0:160 offset1:162
	v_exp_f32_e32 v64, v64
	v_exp_f32_e32 v65, v65
	v_add_f32_e32 v50, v51, v50
	v_add_f32_e32 v50, v138, v50
	v_add_f32_e32 v50, v140, v50
	v_add_f32_e32 v50, v141, v50
	s_waitcnt lgkmcnt(0)
	v_mfma_f32_32x32x16_bf16 v[2:17], v[56:59], v[52:55], v[2:17]
	v_add3_u32 v253, v252, v185, s33
	s_waitcnt vmcnt(2)
	ds_write2_b64 v253, v[102:103], v[104:105] offset1:1
	global_load_dwordx4 v[102:105], v230, s[24:25]
	ds_read2_b64 v[56:59], v66 offset0:164 offset1:166
	v_cvt_pk_bf16_f32 v52, v74, v75
	v_cvt_pk_bf16_f32 v53, v76, v77
	v_cvt_pk_bf16_f32 v54, v78, v79
	v_cvt_pk_bf16_f32 v55, v80, v81
	v_add_f32_e32 v50, v142, v50
	v_add_f32_e32 v50, v143, v50
	s_waitcnt lgkmcnt(0)
	v_mfma_f32_32x32x16_bf16 v[2:17], v[56:59], v[52:55], v[2:17]
	v_add_u32_e32 v253, v252, v180
	s_waitcnt vmcnt(3)
	ds_write_b128 v253, v[106:109]
	global_load_dwordx4 v[106:109], v229, s[12:13]
	ds_read2_b64 v[56:59], v67 offset0:136 offset1:138
	v_add_f32_e32 v50, v144, v50
	v_add_f32_e32 v50, v145, v50
	v_add_f32_e32 v50, v147, v50
	v_add_f32_e32 v50, v148, v50
	v_add_f32_e32 v50, v149, v50
	v_add_f32_e32 v50, v150, v50
	v_mfma_f32_32x32x16_bf16 v[18:33], v[60:63], v[52:55], v[18:33]
	v_add3_u32 v253, v252, v186, s33
	s_waitcnt vmcnt(3)
	ds_write2_b64 v253, v[110:111], v[112:113] offset1:1
	global_load_dwordx4 v[110:113], v231, s[24:25]
	s_add_u32 s12, s12, 0x2000
	s_addc_u32 s13, s13, 0
	s_add_u32 s24, s24, 0x80
	s_addc_u32 s25, s25, 0
	v_cvt_pk_bf16_f32 v52, v139, v51
	v_cvt_pk_bf16_f32 v53, v138, v140
	v_cvt_pk_bf16_f32 v54, v141, v142
	v_cvt_pk_bf16_f32 v55, v143, v144
	v_add_f32_e32 v50, v151, v50
	v_add_f32_e32 v50, v64, v50
	v_add_f32_e32 v50, v65, v50
	s_waitcnt lgkmcnt(0)
	v_mfma_f32_32x32x16_bf16 v[18:33], v[56:59], v[52:55], v[18:33]
	ds_read2_b64 v[56:59], v66 offset0:168 offset1:170
	v_add_f32_e32 v136, v136, v50
	v_cmp_lt_f32_e32 vcc, s20, v50
	s_waitcnt lgkmcnt(0)
	v_mfma_f32_32x32x16_bf16 v[2:17], v[56:59], v[52:55], v[2:17]
	ds_read2_b64 v[56:59], v67 offset0:140 offset1:142
	v_cvt_pk_bf16_f32 v52, v145, v147
	v_cvt_pk_bf16_f32 v53, v148, v149
	v_cvt_pk_bf16_f32 v54, v150, v151
	v_cvt_pk_bf16_f32 v55, v64, v65
	s_waitcnt lgkmcnt(0)
	s_nop 0
	v_mfma_f32_32x32x16_bf16 v[18:33], v[56:59], v[52:55], v[18:33]
	ds_read2_b64 v[56:59], v66 offset0:172 offset1:174
	s_waitcnt lgkmcnt(0)
	v_mfma_f32_32x32x16_bf16 v[2:17], v[56:59], v[52:55], v[2:17]
	s_cbranch_vccz .LBB0_938
	v_mov_b32_e32 v34, v50
	s_nop 1
	v_permlane32_swap_b32_e32 v50, v34
	v_add_f32_e32 v34, v50, v34
	v_log_f32_e32 v35, v34
	v_cmp_lt_f32_e32 vcc, s20, v34
	s_nop 1
	v_cndmask_b32_e32 v35, 0, v35, vcc
	v_exp_f32_e64 v34, -v35
	v_add_f32_e32 v0, v0, v35
	v_xor_b32_e32 v49, 0x80000000, v0
	v_mov_b32_e32 v48, v49
	v_mul_f32_e32 v136, v136, v34
	v_pk_mul_f32 v[32:33], v[32:33], v[34:35] op_sel_hi:[1,0]
	v_pk_mul_f32 v[30:31], v[30:31], v[34:35] op_sel_hi:[1,0]
	v_pk_mul_f32 v[28:29], v[28:29], v[34:35] op_sel_hi:[1,0]
	v_pk_mul_f32 v[26:27], v[26:27], v[34:35] op_sel_hi:[1,0]
	v_pk_mul_f32 v[24:25], v[24:25], v[34:35] op_sel_hi:[1,0]
	v_pk_mul_f32 v[22:23], v[22:23], v[34:35] op_sel_hi:[1,0]
	v_pk_mul_f32 v[20:21], v[20:21], v[34:35] op_sel_hi:[1,0]
	v_pk_mul_f32 v[18:19], v[18:19], v[34:35] op_sel_hi:[1,0]
	v_pk_mul_f32 v[16:17], v[16:17], v[34:35] op_sel_hi:[1,0]
	v_pk_mul_f32 v[14:15], v[14:15], v[34:35] op_sel_hi:[1,0]
	v_pk_mul_f32 v[12:13], v[12:13], v[34:35] op_sel_hi:[1,0]
	v_pk_mul_f32 v[10:11], v[10:11], v[34:35] op_sel_hi:[1,0]
	v_pk_mul_f32 v[8:9], v[8:9], v[34:35] op_sel_hi:[1,0]
	v_pk_mul_f32 v[6:7], v[6:7], v[34:35] op_sel_hi:[1,0]
	v_pk_mul_f32 v[4:5], v[4:5], v[34:35] op_sel_hi:[1,0]
	v_pk_mul_f32 v[2:3], v[2:3], v[34:35] op_sel_hi:[1,0]
	v_mov_b32_e32 v47, v49
	v_mov_b32_e32 v46, v49
	v_mov_b32_e32 v45, v49
	v_mov_b32_e32 v44, v49
	v_mov_b32_e32 v43, v49
	v_mov_b32_e32 v42, v49
	v_mov_b32_e32 v41, v49
	v_mov_b32_e32 v40, v49
	v_mov_b32_e32 v39, v49
	v_mov_b32_e32 v38, v49
	v_mov_b32_e32 v37, v49
	v_mov_b32_e32 v36, v49
	v_mov_b32_e32 v35, v49
	v_mov_b32_e32 v34, v49
	s_branch .LBB0_938
